# f31 + gate epilogue: the two FMAs per element issued as packed f32 pairs (v_pk_fma_f32, clamp verified on the chip)
# speedup vs baseline: 1.0161x; 1.0021x over previous
; __device__ __forceinline__ float sigmoidf_(float x) { return frcp(1.0f + fexp(-x)); }
;     __device__ __forceinline__ void operator()(const Acc& acc, const Unit& u, int wr, int wc, int fr, int fq) const {
;     ...
;             for (int m = 0; m < 4; ++m) { const int row = row0 + ai * HALF + m * 16; const float rs = rsv[ai][m]; unsigned char* rowp = GT + (size_t)row * NGT + colt;
; #pragma unroll
;                 for (int bj = 0; bj < 2; ++bj) { f32x4 v0 = acc[ai][bj][m][0] * rs + bv[bj][0], v1 = acc[ai][bj][m][1] * rs + bv[bj][1];
;                     unsigned q0[4], q1[4];
; #pragma unroll
;                     for (int e = 0; e < 4; ++e) { q0[e] = (unsigned)fmaxf(sigmoidf_(v0[e]) * 255.0f + 0.5f, 1.0f); q1[e] = (unsigned)fmaxf(sigmoidf_(v1[e]) * 255.0f + 0.5f, 1.0f); }
;                     u32x2 w; w.x = q0[0] | (q0[1] << 8) | (q0[2] << 16) | (q0[3] << 24); w.y = q1[0] | (q1[1] << 8) | (q1[2] << 16) | (q1[3] << 24);
;                     *(u32x2*)(rowp + bj * HALF) = w; } }
; template <class Epi, class Sched, bool ALIGN_EPI, bool SP2>
; __device__ __forceinline__ void gemm_phase8(LAS unsigned char* lds, const int K, const Sched& S, const Epi& E) {
;     ...
;         asm volatile("s_nop 15\n\ts_nop 7" ::: "memory");
.LBB0_570:
	s_nop 15
	s_nop 7
	s_mul_i32 s99, s42, 24
	s_add_i32 s99, s99, s0
	s_lshl_b32 s99, s99, 16
	v_lshl_add_u32 v222, v0, 4, s99
	v_lshl_add_u32 v24, s42, 8, v193
	s_lshl_b32 s1, s0, 8
	v_or_b32_e32 v22, 16, v24
	v_or_b32_e32 v20, 32, v24
	v_or_b32_e32 v18, 48, v24
	s_mov_b64 s[42:43], -1
	s_cmp_lt_i32 s0, 24
	v_ashrrev_i32_e32 v25, 31, v24
	v_add_u32_e32 v183, 0x80, v24
	v_add_u32_e32 v182, 0x90, v24
	v_add_u32_e32 v181, 0xa0, v24
	v_add_u32_e32 v180, 0xb0, v24
	v_ashrrev_i32_e32 v23, 31, v22
	v_ashrrev_i32_e32 v21, 31, v20
	v_ashrrev_i32_e32 v19, 31, v18
	s_cbranch_scc0 .LBB0_573
	v_or_b32_e32 v26, s1, v189
	v_ashrrev_i32_e32 v27, 31, v26
	v_mov_b64_e32 v[28:29], s[88:89]
	v_mad_i64_i32 v[30:31], s[42:43], v24, s62, v[28:29]
	v_lshl_add_u64 v[186:187], v[30:31], 0, v[26:27]
	s_mov_b32 s98, 0x3b808081
	v_mul_f32_e32 v2, 0xbfb8aa3b, v242
	v_mul_f32_e32 v3, 0xbfb8aa3b, v243
	v_mul_f32_e32 v4, 0xbfb8aa3b, v244
	v_mul_f32_e32 v5, 0xbfb8aa3b, v245
	v_mul_f32_e32 v6, 0xbfb8aa3b, v238
	v_mul_f32_e32 v7, 0xbfb8aa3b, v239
	v_mul_f32_e32 v8, 0xbfb8aa3b, v240
	v_mul_f32_e32 v9, 0xbfb8aa3b, v241
	v_mul_f32_e32 v10, 0xbfb8aa3b, v234
	v_mul_f32_e32 v11, 0xbfb8aa3b, v235
	v_mul_f32_e32 v12, 0xbfb8aa3b, v236
	v_mul_f32_e32 v13, 0xbfb8aa3b, v237
	v_mul_f32_e32 v14, 0xbfb8aa3b, v230
	v_mul_f32_e32 v15, 0xbfb8aa3b, v231
	v_mul_f32_e32 v16, 0xbfb8aa3b, v232
	v_mul_f32_e32 v17, 0xbfb8aa3b, v233
	v_mul_f32_e32 v30, 0xbb38aa3b, v170
	v_mul_f32_e32 v199, 0xbb38aa3b, v246
	v_mul_f32_e32 v200, 0xbb38aa3b, v247
	v_mul_f32_e32 v184, 0xbb38aa3b, v248
	v_mul_f32_e32 v170, 0xbb38aa3b, v249
	v_mul_f32_e32 v33, 0xbb38aa3b, v250
	v_mul_f32_e32 v32, 0xbb38aa3b, v251
	v_mul_f32_e32 v31, 0xbb38aa3b, v195
	v_pk_fma_f32 v[202:203], v[154:155], v[198:199], v[10:11] op_sel:[0,1,0] op_sel_hi:[1,1,1]
	v_pk_fma_f32 v[204:205], v[156:157], v[198:199], v[12:13] op_sel:[0,1,0] op_sel_hi:[1,1,1]
	v_pk_fma_f32 v[206:207], v[158:159], v[198:199], v[14:15] op_sel:[0,1,0] op_sel_hi:[1,1,1]
	v_pk_fma_f32 v[208:209], v[160:161], v[198:199], v[16:17] op_sel:[0,1,0] op_sel_hi:[1,1,1]
	v_exp_f32_e32 v202, v202
	v_exp_f32_e32 v203, v203
	v_exp_f32_e32 v204, v204
	v_exp_f32_e32 v205, v205
	v_exp_f32_e32 v206, v206
	v_exp_f32_e32 v207, v207
	v_exp_f32_e32 v208, v208
	v_exp_f32_e32 v209, v209
	s_nop 0
	v_pk_fma_f32 v[202:203], v[202:203], s[98:99], s[98:99] op_sel_hi:[1,0,0] clamp
	v_pk_fma_f32 v[204:205], v[204:205], s[98:99], s[98:99] op_sel_hi:[1,0,0] clamp
	v_pk_fma_f32 v[206:207], v[206:207], s[98:99], s[98:99] op_sel_hi:[1,0,0] clamp
	v_pk_fma_f32 v[208:209], v[208:209], s[98:99], s[98:99] op_sel_hi:[1,0,0] clamp
	v_rcp_f32_e32 v202, v202
	v_rcp_f32_e32 v203, v203
	v_rcp_f32_e32 v204, v204
	v_rcp_f32_e32 v205, v205
	v_rcp_f32_e32 v206, v206
	v_rcp_f32_e32 v207, v207
	v_rcp_f32_e32 v208, v208
	v_rcp_f32_e32 v209, v209
	s_nop 0
	v_cvt_pk_u8_f32 v210, v206, 0, 0
	v_cvt_pk_u8_f32 v210, v207, 1, v210
	v_cvt_pk_u8_f32 v210, v208, 2, v210
	v_cvt_pk_u8_f32 v210, v209, 3, v210
	v_cvt_pk_u8_f32 v211, v202, 0, 0
	v_cvt_pk_u8_f32 v211, v203, 1, v211
	v_cvt_pk_u8_f32 v211, v204, 2, v211
	v_cvt_pk_u8_f32 v211, v205, 3, v211
	v_pk_fma_f32 v[202:203], v[146:147], v[198:199], v[2:3] op_sel:[0,1,0] op_sel_hi:[1,1,1]
	v_pk_fma_f32 v[204:205], v[148:149], v[198:199], v[4:5] op_sel:[0,1,0] op_sel_hi:[1,1,1]
	v_pk_fma_f32 v[206:207], v[150:151], v[198:199], v[6:7] op_sel:[0,1,0] op_sel_hi:[1,1,1]
	v_pk_fma_f32 v[208:209], v[152:153], v[198:199], v[8:9] op_sel:[0,1,0] op_sel_hi:[1,1,1]
	v_exp_f32_e32 v202, v202
	v_exp_f32_e32 v203, v203
	v_exp_f32_e32 v204, v204
	v_exp_f32_e32 v205, v205
	v_exp_f32_e32 v206, v206
	v_exp_f32_e32 v207, v207
	v_exp_f32_e32 v208, v208
	v_exp_f32_e32 v209, v209
	s_nop 0
	v_pk_fma_f32 v[202:203], v[202:203], s[98:99], s[98:99] op_sel_hi:[1,0,0] clamp
	v_pk_fma_f32 v[204:205], v[204:205], s[98:99], s[98:99] op_sel_hi:[1,0,0] clamp
	v_pk_fma_f32 v[206:207], v[206:207], s[98:99], s[98:99] op_sel_hi:[1,0,0] clamp
	v_pk_fma_f32 v[208:209], v[208:209], s[98:99], s[98:99] op_sel_hi:[1,0,0] clamp
	v_rcp_f32_e32 v202, v202
	v_rcp_f32_e32 v203, v203
	v_rcp_f32_e32 v204, v204
	v_rcp_f32_e32 v205, v205
	v_rcp_f32_e32 v206, v206
	v_rcp_f32_e32 v207, v207
	v_rcp_f32_e32 v208, v208
	v_rcp_f32_e32 v209, v209
	s_nop 0
	v_cvt_pk_u8_f32 v212, v206, 0, 0
	v_cvt_pk_u8_f32 v212, v207, 1, v212
	v_cvt_pk_u8_f32 v212, v208, 2, v212
	v_cvt_pk_u8_f32 v212, v209, 3, v212
	v_cvt_pk_u8_f32 v213, v202, 0, 0
	v_cvt_pk_u8_f32 v213, v203, 1, v213
	v_cvt_pk_u8_f32 v213, v204, 2, v213
	v_cvt_pk_u8_f32 v213, v205, 3, v213
	global_store_dwordx4 v222, v[210:213], s[88:89]
	v_pk_fma_f32 v[202:203], v[138:139], v[200:201], v[10:11] op_sel:[0,0,0] op_sel_hi:[1,0,1]
	v_pk_fma_f32 v[204:205], v[140:141], v[200:201], v[12:13] op_sel:[0,0,0] op_sel_hi:[1,0,1]
	v_pk_fma_f32 v[206:207], v[142:143], v[200:201], v[14:15] op_sel:[0,0,0] op_sel_hi:[1,0,1]
	v_pk_fma_f32 v[208:209], v[144:145], v[200:201], v[16:17] op_sel:[0,0,0] op_sel_hi:[1,0,1]
	v_exp_f32_e32 v202, v202
	v_exp_f32_e32 v203, v203
	v_exp_f32_e32 v204, v204
	v_exp_f32_e32 v205, v205
	v_exp_f32_e32 v206, v206
	v_exp_f32_e32 v207, v207
	v_exp_f32_e32 v208, v208
	v_exp_f32_e32 v209, v209
	s_nop 0
	v_pk_fma_f32 v[202:203], v[202:203], s[98:99], s[98:99] op_sel_hi:[1,0,0] clamp
	v_pk_fma_f32 v[204:205], v[204:205], s[98:99], s[98:99] op_sel_hi:[1,0,0] clamp
	v_pk_fma_f32 v[206:207], v[206:207], s[98:99], s[98:99] op_sel_hi:[1,0,0] clamp
	v_pk_fma_f32 v[208:209], v[208:209], s[98:99], s[98:99] op_sel_hi:[1,0,0] clamp
	v_rcp_f32_e32 v202, v202
	v_rcp_f32_e32 v203, v203
	v_rcp_f32_e32 v204, v204
	v_rcp_f32_e32 v205, v205
	v_rcp_f32_e32 v206, v206
	v_rcp_f32_e32 v207, v207
; __device__ __forceinline__ float sigmoidf_(float x) { return frcp(1.0f + fexp(-x)); }
;     __device__ __forceinline__ void operator()(const Acc& acc, const Unit& u, int wr, int wc, int fr, int fq) const {
;     ...
;             for (int m = 0; m < 4; ++m) { const int row = row0 + ai * HALF + m * 16; const float rs = rsv[ai][m]; unsigned char* rowp = GT + (size_t)row * NGT + colt;
; #pragma unroll
;                 for (int bj = 0; bj < 2; ++bj) { f32x4 v0 = acc[ai][bj][m][0] * rs + bv[bj][0], v1 = acc[ai][bj][m][1] * rs + bv[bj][1];
;                     unsigned q0[4], q1[4];
; #pragma unroll
;                     for (int e = 0; e < 4; ++e) { q0[e] = (unsigned)fmaxf(sigmoidf_(v0[e]) * 255.0f + 0.5f, 1.0f); q1[e] = (unsigned)fmaxf(sigmoidf_(v1[e]) * 255.0f + 0.5f, 1.0f); }
;                     u32x2 w; w.x = q0[0] | (q0[1] << 8) | (q0[2] << 16) | (q0[3] << 24); w.y = q1[0] | (q1[1] << 8) | (q1[2] << 16) | (q1[3] << 24);
;                     *(u32x2*)(rowp + bj * HALF) = w; } }
	v_rcp_f32_e32 v208, v208
	v_rcp_f32_e32 v209, v209
	s_nop 0
	v_cvt_pk_u8_f32 v214, v206, 0, 0
	v_cvt_pk_u8_f32 v214, v207, 1, v214
	v_cvt_pk_u8_f32 v214, v208, 2, v214
	v_cvt_pk_u8_f32 v214, v209, 3, v214
	v_cvt_pk_u8_f32 v215, v202, 0, 0
	v_cvt_pk_u8_f32 v215, v203, 1, v215
	v_cvt_pk_u8_f32 v215, v204, 2, v215
	v_cvt_pk_u8_f32 v215, v205, 3, v215
	v_mad_i64_i32 v[186:187], s[42:43], v22, s62, v[28:29]
	v_lshl_add_u64 v[186:187], v[186:187], 0, v[26:27]
	v_pk_fma_f32 v[202:203], v[130:131], v[200:201], v[2:3] op_sel:[0,0,0] op_sel_hi:[1,0,1]
	v_pk_fma_f32 v[204:205], v[132:133], v[200:201], v[4:5] op_sel:[0,0,0] op_sel_hi:[1,0,1]
	v_pk_fma_f32 v[206:207], v[134:135], v[200:201], v[6:7] op_sel:[0,0,0] op_sel_hi:[1,0,1]
	v_pk_fma_f32 v[208:209], v[136:137], v[200:201], v[8:9] op_sel:[0,0,0] op_sel_hi:[1,0,1]
	v_exp_f32_e32 v202, v202
	v_exp_f32_e32 v203, v203
	v_exp_f32_e32 v204, v204
	v_exp_f32_e32 v205, v205
	v_exp_f32_e32 v206, v206
	v_exp_f32_e32 v207, v207
	v_exp_f32_e32 v208, v208
	v_exp_f32_e32 v209, v209
	s_nop 0
	v_pk_fma_f32 v[202:203], v[202:203], s[98:99], s[98:99] op_sel_hi:[1,0,0] clamp
	v_pk_fma_f32 v[204:205], v[204:205], s[98:99], s[98:99] op_sel_hi:[1,0,0] clamp
	v_pk_fma_f32 v[206:207], v[206:207], s[98:99], s[98:99] op_sel_hi:[1,0,0] clamp
	v_pk_fma_f32 v[208:209], v[208:209], s[98:99], s[98:99] op_sel_hi:[1,0,0] clamp
	v_rcp_f32_e32 v202, v202
	v_rcp_f32_e32 v203, v203
	v_rcp_f32_e32 v204, v204
	v_rcp_f32_e32 v205, v205
	v_rcp_f32_e32 v206, v206
	v_rcp_f32_e32 v207, v207
	v_rcp_f32_e32 v208, v208
	v_rcp_f32_e32 v209, v209
	s_nop 0
	v_cvt_pk_u8_f32 v216, v206, 0, 0
	v_cvt_pk_u8_f32 v216, v207, 1, v216
	v_cvt_pk_u8_f32 v216, v208, 2, v216
	v_cvt_pk_u8_f32 v216, v209, 3, v216
	v_cvt_pk_u8_f32 v217, v202, 0, 0
	v_cvt_pk_u8_f32 v217, v203, 1, v217
	v_cvt_pk_u8_f32 v217, v204, 2, v217
	v_cvt_pk_u8_f32 v217, v205, 3, v217
	v_add_u32_e32 v223, 0x2000, v222
	global_store_dwordx4 v223, v[214:217], s[88:89]
	v_pk_fma_f32 v[202:203], v[122:123], v[184:185], v[10:11] op_sel:[0,0,0] op_sel_hi:[1,0,1]
	v_pk_fma_f32 v[204:205], v[124:125], v[184:185], v[12:13] op_sel:[0,0,0] op_sel_hi:[1,0,1]
	v_pk_fma_f32 v[206:207], v[126:127], v[184:185], v[14:15] op_sel:[0,0,0] op_sel_hi:[1,0,1]
	v_pk_fma_f32 v[208:209], v[128:129], v[184:185], v[16:17] op_sel:[0,0,0] op_sel_hi:[1,0,1]
	v_exp_f32_e32 v202, v202
	v_exp_f32_e32 v203, v203
	v_exp_f32_e32 v204, v204
	v_exp_f32_e32 v205, v205
	v_exp_f32_e32 v206, v206
	v_exp_f32_e32 v207, v207
	v_exp_f32_e32 v208, v208
	v_exp_f32_e32 v209, v209
	s_nop 0
	v_pk_fma_f32 v[202:203], v[202:203], s[98:99], s[98:99] op_sel_hi:[1,0,0] clamp
	v_pk_fma_f32 v[204:205], v[204:205], s[98:99], s[98:99] op_sel_hi:[1,0,0] clamp
	v_pk_fma_f32 v[206:207], v[206:207], s[98:99], s[98:99] op_sel_hi:[1,0,0] clamp
	v_pk_fma_f32 v[208:209], v[208:209], s[98:99], s[98:99] op_sel_hi:[1,0,0] clamp
	v_rcp_f32_e32 v202, v202
	v_rcp_f32_e32 v203, v203
	v_rcp_f32_e32 v204, v204
	v_rcp_f32_e32 v205, v205
	v_rcp_f32_e32 v206, v206
	v_rcp_f32_e32 v207, v207
	v_rcp_f32_e32 v208, v208
	v_rcp_f32_e32 v209, v209
	s_nop 0
	v_cvt_pk_u8_f32 v218, v206, 0, 0
	v_cvt_pk_u8_f32 v218, v207, 1, v218
	v_cvt_pk_u8_f32 v218, v208, 2, v218
	v_cvt_pk_u8_f32 v218, v209, 3, v218
	v_cvt_pk_u8_f32 v219, v202, 0, 0
	v_cvt_pk_u8_f32 v219, v203, 1, v219
	v_cvt_pk_u8_f32 v219, v204, 2, v219
	v_cvt_pk_u8_f32 v219, v205, 3, v219
	v_mad_i64_i32 v[186:187], s[42:43], v20, s62, v[28:29]
	v_lshl_add_u64 v[186:187], v[186:187], 0, v[26:27]
	v_pk_fma_f32 v[202:203], v[114:115], v[184:185], v[2:3] op_sel:[0,0,0] op_sel_hi:[1,0,1]
	v_pk_fma_f32 v[204:205], v[116:117], v[184:185], v[4:5] op_sel:[0,0,0] op_sel_hi:[1,0,1]
	v_pk_fma_f32 v[206:207], v[118:119], v[184:185], v[6:7] op_sel:[0,0,0] op_sel_hi:[1,0,1]
	v_pk_fma_f32 v[208:209], v[120:121], v[184:185], v[8:9] op_sel:[0,0,0] op_sel_hi:[1,0,1]
	v_exp_f32_e32 v202, v202
	v_exp_f32_e32 v203, v203
	v_exp_f32_e32 v204, v204
	v_exp_f32_e32 v205, v205
	v_exp_f32_e32 v206, v206
	v_exp_f32_e32 v207, v207
	v_exp_f32_e32 v208, v208
	v_exp_f32_e32 v209, v209
	s_nop 0
	v_pk_fma_f32 v[202:203], v[202:203], s[98:99], s[98:99] op_sel_hi:[1,0,0] clamp
	v_pk_fma_f32 v[204:205], v[204:205], s[98:99], s[98:99] op_sel_hi:[1,0,0] clamp
	v_pk_fma_f32 v[206:207], v[206:207], s[98:99], s[98:99] op_sel_hi:[1,0,0] clamp
	v_pk_fma_f32 v[208:209], v[208:209], s[98:99], s[98:99] op_sel_hi:[1,0,0] clamp
	v_rcp_f32_e32 v202, v202
	v_rcp_f32_e32 v203, v203
	v_rcp_f32_e32 v204, v204
	v_rcp_f32_e32 v205, v205
	v_rcp_f32_e32 v206, v206
	v_rcp_f32_e32 v207, v207
	v_rcp_f32_e32 v208, v208
	v_rcp_f32_e32 v209, v209
	s_nop 0
	v_cvt_pk_u8_f32 v220, v206, 0, 0
	v_cvt_pk_u8_f32 v220, v207, 1, v220
	v_cvt_pk_u8_f32 v220, v208, 2, v220
	v_cvt_pk_u8_f32 v220, v209, 3, v220
	v_cvt_pk_u8_f32 v221, v202, 0, 0
	v_cvt_pk_u8_f32 v221, v203, 1, v221
	v_cvt_pk_u8_f32 v221, v204, 2, v221
	v_cvt_pk_u8_f32 v221, v205, 3, v221
	v_add_u32_e32 v223, 0x4000, v222
	global_store_dwordx4 v223, v[218:221], s[88:89]
	v_pk_fma_f32 v[202:203], v[106:107], v[170:171], v[10:11] op_sel:[0,0,0] op_sel_hi:[1,0,1]
	v_pk_fma_f32 v[204:205], v[108:109], v[170:171], v[12:13] op_sel:[0,0,0] op_sel_hi:[1,0,1]
	v_pk_fma_f32 v[206:207], v[110:111], v[170:171], v[14:15] op_sel:[0,0,0] op_sel_hi:[1,0,1]
	v_pk_fma_f32 v[208:209], v[112:113], v[170:171], v[16:17] op_sel:[0,0,0] op_sel_hi:[1,0,1]
	v_exp_f32_e32 v202, v202
	v_exp_f32_e32 v203, v203
	v_exp_f32_e32 v204, v204
	v_exp_f32_e32 v205, v205
	v_exp_f32_e32 v206, v206
	v_exp_f32_e32 v207, v207
	v_exp_f32_e32 v208, v208
	v_exp_f32_e32 v209, v209
	s_nop 0
	v_pk_fma_f32 v[202:203], v[202:203], s[98:99], s[98:99] op_sel_hi:[1,0,0] clamp
; __device__ __forceinline__ float sigmoidf_(float x) { return frcp(1.0f + fexp(-x)); }
;     __device__ __forceinline__ void operator()(const Acc& acc, const Unit& u, int wr, int wc, int fr, int fq) const {
;     ...
;             for (int m = 0; m < 4; ++m) { const int row = row0 + ai * HALF + m * 16; const float rs = rsv[ai][m]; unsigned char* rowp = GT + (size_t)row * NGT + colt;
; #pragma unroll
;                 for (int bj = 0; bj < 2; ++bj) { f32x4 v0 = acc[ai][bj][m][0] * rs + bv[bj][0], v1 = acc[ai][bj][m][1] * rs + bv[bj][1];
;                     unsigned q0[4], q1[4];
; #pragma unroll
;                     for (int e = 0; e < 4; ++e) { q0[e] = (unsigned)fmaxf(sigmoidf_(v0[e]) * 255.0f + 0.5f, 1.0f); q1[e] = (unsigned)fmaxf(sigmoidf_(v1[e]) * 255.0f + 0.5f, 1.0f); }
;                     u32x2 w; w.x = q0[0] | (q0[1] << 8) | (q0[2] << 16) | (q0[3] << 24); w.y = q1[0] | (q1[1] << 8) | (q1[2] << 16) | (q1[3] << 24);
;                     *(u32x2*)(rowp + bj * HALF) = w; } }
	v_pk_fma_f32 v[204:205], v[204:205], s[98:99], s[98:99] op_sel_hi:[1,0,0] clamp
	v_pk_fma_f32 v[206:207], v[206:207], s[98:99], s[98:99] op_sel_hi:[1,0,0] clamp
	v_pk_fma_f32 v[208:209], v[208:209], s[98:99], s[98:99] op_sel_hi:[1,0,0] clamp
	v_rcp_f32_e32 v202, v202
	v_rcp_f32_e32 v203, v203
	v_rcp_f32_e32 v204, v204
	v_rcp_f32_e32 v205, v205
	v_rcp_f32_e32 v206, v206
	v_rcp_f32_e32 v207, v207
	v_rcp_f32_e32 v208, v208
	v_rcp_f32_e32 v209, v209
	s_nop 0
	v_cvt_pk_u8_f32 v210, v206, 0, 0
	v_cvt_pk_u8_f32 v210, v207, 1, v210
	v_cvt_pk_u8_f32 v210, v208, 2, v210
	v_cvt_pk_u8_f32 v210, v209, 3, v210
	v_cvt_pk_u8_f32 v211, v202, 0, 0
	v_cvt_pk_u8_f32 v211, v203, 1, v211
	v_cvt_pk_u8_f32 v211, v204, 2, v211
	v_cvt_pk_u8_f32 v211, v205, 3, v211
	v_mad_i64_i32 v[184:185], s[42:43], v18, s62, v[28:29]
	v_lshl_add_u64 v[184:185], v[184:185], 0, v[26:27]
	v_pk_fma_f32 v[202:203], v[98:99], v[170:171], v[2:3] op_sel:[0,0,0] op_sel_hi:[1,0,1]
	v_pk_fma_f32 v[204:205], v[100:101], v[170:171], v[4:5] op_sel:[0,0,0] op_sel_hi:[1,0,1]
	v_pk_fma_f32 v[206:207], v[102:103], v[170:171], v[6:7] op_sel:[0,0,0] op_sel_hi:[1,0,1]
	v_pk_fma_f32 v[208:209], v[104:105], v[170:171], v[8:9] op_sel:[0,0,0] op_sel_hi:[1,0,1]
	v_exp_f32_e32 v202, v202
	v_exp_f32_e32 v203, v203
	v_exp_f32_e32 v204, v204
	v_exp_f32_e32 v205, v205
	v_exp_f32_e32 v206, v206
	v_exp_f32_e32 v207, v207
	v_exp_f32_e32 v208, v208
	v_exp_f32_e32 v209, v209
	s_nop 0
	v_pk_fma_f32 v[202:203], v[202:203], s[98:99], s[98:99] op_sel_hi:[1,0,0] clamp
	v_pk_fma_f32 v[204:205], v[204:205], s[98:99], s[98:99] op_sel_hi:[1,0,0] clamp
	v_pk_fma_f32 v[206:207], v[206:207], s[98:99], s[98:99] op_sel_hi:[1,0,0] clamp
	v_pk_fma_f32 v[208:209], v[208:209], s[98:99], s[98:99] op_sel_hi:[1,0,0] clamp
	v_rcp_f32_e32 v202, v202
	v_rcp_f32_e32 v203, v203
	v_rcp_f32_e32 v204, v204
	v_rcp_f32_e32 v205, v205
	v_rcp_f32_e32 v206, v206
	v_rcp_f32_e32 v207, v207
	v_rcp_f32_e32 v208, v208
	v_rcp_f32_e32 v209, v209
	s_nop 0
	v_cvt_pk_u8_f32 v212, v206, 0, 0
	v_cvt_pk_u8_f32 v212, v207, 1, v212
	v_cvt_pk_u8_f32 v212, v208, 2, v212
	v_cvt_pk_u8_f32 v212, v209, 3, v212
	v_cvt_pk_u8_f32 v213, v202, 0, 0
	v_cvt_pk_u8_f32 v213, v203, 1, v213
	v_cvt_pk_u8_f32 v213, v204, 2, v213
	v_cvt_pk_u8_f32 v213, v205, 3, v213
	v_add_u32_e32 v223, 0x6000, v222
	global_store_dwordx4 v223, v[210:213], s[88:89]
	v_pk_fma_f32 v[202:203], v[90:91], v[32:33], v[10:11] op_sel:[0,1,0] op_sel_hi:[1,1,1]
	v_pk_fma_f32 v[204:205], v[92:93], v[32:33], v[12:13] op_sel:[0,1,0] op_sel_hi:[1,1,1]
	v_pk_fma_f32 v[206:207], v[94:95], v[32:33], v[14:15] op_sel:[0,1,0] op_sel_hi:[1,1,1]
	v_pk_fma_f32 v[208:209], v[96:97], v[32:33], v[16:17] op_sel:[0,1,0] op_sel_hi:[1,1,1]
	v_exp_f32_e32 v202, v202
	v_exp_f32_e32 v203, v203
	v_exp_f32_e32 v204, v204
	v_exp_f32_e32 v205, v205
	v_exp_f32_e32 v206, v206
	v_exp_f32_e32 v207, v207
	v_exp_f32_e32 v208, v208
	v_exp_f32_e32 v209, v209
	s_nop 0
	v_pk_fma_f32 v[202:203], v[202:203], s[98:99], s[98:99] op_sel_hi:[1,0,0] clamp
	v_pk_fma_f32 v[204:205], v[204:205], s[98:99], s[98:99] op_sel_hi:[1,0,0] clamp
	v_pk_fma_f32 v[206:207], v[206:207], s[98:99], s[98:99] op_sel_hi:[1,0,0] clamp
	v_pk_fma_f32 v[208:209], v[208:209], s[98:99], s[98:99] op_sel_hi:[1,0,0] clamp
	v_rcp_f32_e32 v202, v202
	v_rcp_f32_e32 v203, v203
	v_rcp_f32_e32 v204, v204
	v_rcp_f32_e32 v205, v205
	v_rcp_f32_e32 v206, v206
	v_rcp_f32_e32 v207, v207
	v_rcp_f32_e32 v208, v208
	v_rcp_f32_e32 v209, v209
	s_nop 0
	v_cvt_pk_u8_f32 v214, v206, 0, 0
	v_cvt_pk_u8_f32 v214, v207, 1, v214
	v_cvt_pk_u8_f32 v214, v208, 2, v214
	v_cvt_pk_u8_f32 v214, v209, 3, v214
	v_cvt_pk_u8_f32 v215, v202, 0, 0
	v_cvt_pk_u8_f32 v215, v203, 1, v215
	v_cvt_pk_u8_f32 v215, v204, 2, v215
	v_cvt_pk_u8_f32 v215, v205, 3, v215
	v_mad_i64_i32 v[184:185], s[42:43], v183, s62, v[28:29]
	v_lshl_add_u64 v[184:185], v[184:185], 0, v[26:27]
	v_pk_fma_f32 v[202:203], v[82:83], v[32:33], v[2:3] op_sel:[0,1,0] op_sel_hi:[1,1,1]
	v_pk_fma_f32 v[204:205], v[84:85], v[32:33], v[4:5] op_sel:[0,1,0] op_sel_hi:[1,1,1]
	v_pk_fma_f32 v[206:207], v[86:87], v[32:33], v[6:7] op_sel:[0,1,0] op_sel_hi:[1,1,1]
	v_pk_fma_f32 v[208:209], v[88:89], v[32:33], v[8:9] op_sel:[0,1,0] op_sel_hi:[1,1,1]
	v_exp_f32_e32 v202, v202
	v_exp_f32_e32 v203, v203
	v_exp_f32_e32 v204, v204
	v_exp_f32_e32 v205, v205
	v_exp_f32_e32 v206, v206
	v_exp_f32_e32 v207, v207
	v_exp_f32_e32 v208, v208
	v_exp_f32_e32 v209, v209
	s_nop 0
	v_pk_fma_f32 v[202:203], v[202:203], s[98:99], s[98:99] op_sel_hi:[1,0,0] clamp
	v_pk_fma_f32 v[204:205], v[204:205], s[98:99], s[98:99] op_sel_hi:[1,0,0] clamp
	v_pk_fma_f32 v[206:207], v[206:207], s[98:99], s[98:99] op_sel_hi:[1,0,0] clamp
	v_pk_fma_f32 v[208:209], v[208:209], s[98:99], s[98:99] op_sel_hi:[1,0,0] clamp
	v_rcp_f32_e32 v202, v202
	v_rcp_f32_e32 v203, v203
	v_rcp_f32_e32 v204, v204
	v_rcp_f32_e32 v205, v205
	v_rcp_f32_e32 v206, v206
	v_rcp_f32_e32 v207, v207
	v_rcp_f32_e32 v208, v208
	v_rcp_f32_e32 v209, v209
	s_nop 0
	v_cvt_pk_u8_f32 v216, v206, 0, 0
	v_cvt_pk_u8_f32 v216, v207, 1, v216
	v_cvt_pk_u8_f32 v216, v208, 2, v216
	v_cvt_pk_u8_f32 v216, v209, 3, v216
	v_cvt_pk_u8_f32 v217, v202, 0, 0
	v_cvt_pk_u8_f32 v217, v203, 1, v217
	v_cvt_pk_u8_f32 v217, v204, 2, v217
	v_cvt_pk_u8_f32 v217, v205, 3, v217
	v_add_u32_e32 v223, 0x8000, v222
	global_store_dwordx4 v223, v[214:217], s[88:89]
	v_pk_fma_f32 v[202:203], v[74:75], v[32:33], v[10:11] op_sel:[0,0,0] op_sel_hi:[1,0,1]
	v_pk_fma_f32 v[204:205], v[76:77], v[32:33], v[12:13] op_sel:[0,0,0] op_sel_hi:[1,0,1]
	v_pk_fma_f32 v[206:207], v[78:79], v[32:33], v[14:15] op_sel:[0,0,0] op_sel_hi:[1,0,1]
	v_pk_fma_f32 v[208:209], v[80:81], v[32:33], v[16:17] op_sel:[0,0,0] op_sel_hi:[1,0,1]
; __device__ __forceinline__ float sigmoidf_(float x) { return frcp(1.0f + fexp(-x)); }
;     __device__ __forceinline__ void operator()(const Acc& acc, const Unit& u, int wr, int wc, int fr, int fq) const {
;     ...
;             for (int m = 0; m < 4; ++m) { const int row = row0 + ai * HALF + m * 16; const float rs = rsv[ai][m]; unsigned char* rowp = GT + (size_t)row * NGT + colt;
; #pragma unroll
;                 for (int bj = 0; bj < 2; ++bj) { f32x4 v0 = acc[ai][bj][m][0] * rs + bv[bj][0], v1 = acc[ai][bj][m][1] * rs + bv[bj][1];
;                     unsigned q0[4], q1[4];
; #pragma unroll
;                     for (int e = 0; e < 4; ++e) { q0[e] = (unsigned)fmaxf(sigmoidf_(v0[e]) * 255.0f + 0.5f, 1.0f); q1[e] = (unsigned)fmaxf(sigmoidf_(v1[e]) * 255.0f + 0.5f, 1.0f); }
;                     u32x2 w; w.x = q0[0] | (q0[1] << 8) | (q0[2] << 16) | (q0[3] << 24); w.y = q1[0] | (q1[1] << 8) | (q1[2] << 16) | (q1[3] << 24);
;                     *(u32x2*)(rowp + bj * HALF) = w; } }
	v_exp_f32_e32 v202, v202
	v_exp_f32_e32 v203, v203
	v_exp_f32_e32 v204, v204
	v_exp_f32_e32 v205, v205
	v_exp_f32_e32 v206, v206
	v_exp_f32_e32 v207, v207
	v_exp_f32_e32 v208, v208
	v_exp_f32_e32 v209, v209
	s_nop 0
	v_pk_fma_f32 v[202:203], v[202:203], s[98:99], s[98:99] op_sel_hi:[1,0,0] clamp
	v_pk_fma_f32 v[204:205], v[204:205], s[98:99], s[98:99] op_sel_hi:[1,0,0] clamp
	v_pk_fma_f32 v[206:207], v[206:207], s[98:99], s[98:99] op_sel_hi:[1,0,0] clamp
	v_pk_fma_f32 v[208:209], v[208:209], s[98:99], s[98:99] op_sel_hi:[1,0,0] clamp
	v_rcp_f32_e32 v202, v202
	v_rcp_f32_e32 v203, v203
	v_rcp_f32_e32 v204, v204
	v_rcp_f32_e32 v205, v205
	v_rcp_f32_e32 v206, v206
	v_rcp_f32_e32 v207, v207
	v_rcp_f32_e32 v208, v208
	v_rcp_f32_e32 v209, v209
	s_nop 0
	v_cvt_pk_u8_f32 v218, v206, 0, 0
	v_cvt_pk_u8_f32 v218, v207, 1, v218
	v_cvt_pk_u8_f32 v218, v208, 2, v218
	v_cvt_pk_u8_f32 v218, v209, 3, v218
	v_cvt_pk_u8_f32 v219, v202, 0, 0
	v_cvt_pk_u8_f32 v219, v203, 1, v219
	v_cvt_pk_u8_f32 v219, v204, 2, v219
	v_cvt_pk_u8_f32 v219, v205, 3, v219
	v_mad_i64_i32 v[184:185], s[42:43], v182, s62, v[28:29]
	v_lshl_add_u64 v[184:185], v[184:185], 0, v[26:27]
	v_pk_fma_f32 v[202:203], v[66:67], v[32:33], v[2:3] op_sel:[0,0,0] op_sel_hi:[1,0,1]
	v_pk_fma_f32 v[204:205], v[68:69], v[32:33], v[4:5] op_sel:[0,0,0] op_sel_hi:[1,0,1]
	v_pk_fma_f32 v[206:207], v[70:71], v[32:33], v[6:7] op_sel:[0,0,0] op_sel_hi:[1,0,1]
	v_pk_fma_f32 v[208:209], v[72:73], v[32:33], v[8:9] op_sel:[0,0,0] op_sel_hi:[1,0,1]
	v_exp_f32_e32 v202, v202
	v_exp_f32_e32 v203, v203
	v_exp_f32_e32 v204, v204
	v_exp_f32_e32 v205, v205
	v_exp_f32_e32 v206, v206
	v_exp_f32_e32 v207, v207
	v_exp_f32_e32 v208, v208
	v_exp_f32_e32 v209, v209
	s_nop 0
	v_pk_fma_f32 v[202:203], v[202:203], s[98:99], s[98:99] op_sel_hi:[1,0,0] clamp
	v_pk_fma_f32 v[204:205], v[204:205], s[98:99], s[98:99] op_sel_hi:[1,0,0] clamp
	v_pk_fma_f32 v[206:207], v[206:207], s[98:99], s[98:99] op_sel_hi:[1,0,0] clamp
	v_pk_fma_f32 v[208:209], v[208:209], s[98:99], s[98:99] op_sel_hi:[1,0,0] clamp
	v_rcp_f32_e32 v202, v202
	v_rcp_f32_e32 v203, v203
	v_rcp_f32_e32 v204, v204
	v_rcp_f32_e32 v205, v205
	v_rcp_f32_e32 v206, v206
	v_rcp_f32_e32 v207, v207
	v_rcp_f32_e32 v208, v208
	v_rcp_f32_e32 v209, v209
	s_nop 0
	v_cvt_pk_u8_f32 v220, v206, 0, 0
	v_cvt_pk_u8_f32 v220, v207, 1, v220
	v_cvt_pk_u8_f32 v220, v208, 2, v220
	v_cvt_pk_u8_f32 v220, v209, 3, v220
	v_cvt_pk_u8_f32 v221, v202, 0, 0
	v_cvt_pk_u8_f32 v221, v203, 1, v221
	v_cvt_pk_u8_f32 v221, v204, 2, v221
	v_cvt_pk_u8_f32 v221, v205, 3, v221
	v_add_u32_e32 v223, 0xa000, v222
	global_store_dwordx4 v223, v[218:221], s[88:89]
	v_mad_i64_i32 v[32:33], s[42:43], v181, s62, v[28:29]
	v_pk_fma_f32 v[202:203], v[58:59], v[30:31], v[10:11] op_sel:[0,1,0] op_sel_hi:[1,1,1]
	v_pk_fma_f32 v[204:205], v[60:61], v[30:31], v[12:13] op_sel:[0,1,0] op_sel_hi:[1,1,1]
	v_pk_fma_f32 v[206:207], v[62:63], v[30:31], v[14:15] op_sel:[0,1,0] op_sel_hi:[1,1,1]
	v_pk_fma_f32 v[208:209], v[64:65], v[30:31], v[16:17] op_sel:[0,1,0] op_sel_hi:[1,1,1]
	v_exp_f32_e32 v202, v202
	v_exp_f32_e32 v203, v203
	v_exp_f32_e32 v204, v204
	v_exp_f32_e32 v205, v205
	v_exp_f32_e32 v206, v206
	v_exp_f32_e32 v207, v207
	v_exp_f32_e32 v208, v208
	v_exp_f32_e32 v209, v209
	s_nop 0
	v_pk_fma_f32 v[202:203], v[202:203], s[98:99], s[98:99] op_sel_hi:[1,0,0] clamp
	v_pk_fma_f32 v[204:205], v[204:205], s[98:99], s[98:99] op_sel_hi:[1,0,0] clamp
	v_pk_fma_f32 v[206:207], v[206:207], s[98:99], s[98:99] op_sel_hi:[1,0,0] clamp
	v_pk_fma_f32 v[208:209], v[208:209], s[98:99], s[98:99] op_sel_hi:[1,0,0] clamp
	v_rcp_f32_e32 v202, v202
	v_rcp_f32_e32 v203, v203
	v_rcp_f32_e32 v204, v204
	v_rcp_f32_e32 v205, v205
	v_rcp_f32_e32 v206, v206
	v_rcp_f32_e32 v207, v207
	v_rcp_f32_e32 v208, v208
	v_rcp_f32_e32 v209, v209
	s_nop 0
	v_cvt_pk_u8_f32 v210, v206, 0, 0
	v_cvt_pk_u8_f32 v210, v207, 1, v210
	v_cvt_pk_u8_f32 v210, v208, 2, v210
	v_cvt_pk_u8_f32 v210, v209, 3, v210
	v_cvt_pk_u8_f32 v211, v202, 0, 0
	v_cvt_pk_u8_f32 v211, v203, 1, v211
	v_cvt_pk_u8_f32 v211, v204, 2, v211
	v_cvt_pk_u8_f32 v211, v205, 3, v211
	v_mad_i64_i32 v[28:29], s[42:43], v180, s62, v[28:29]
	v_lshl_add_u64 v[32:33], v[32:33], 0, v[26:27]
	v_lshl_add_u64 v[26:27], v[28:29], 0, v[26:27]
	v_pk_fma_f32 v[202:203], v[42:43], v[30:31], v[10:11] op_sel:[0,0,0] op_sel_hi:[1,0,1]
; __device__ __forceinline__ float sigmoidf_(float x) { return frcp(1.0f + fexp(-x)); }
;     __device__ __forceinline__ void operator()(const Acc& acc, const Unit& u, int wr, int wc, int fr, int fq) const {
;     ...
;             for (int m = 0; m < 4; ++m) { const int row = row0 + ai * HALF + m * 16; const float rs = rsv[ai][m]; unsigned char* rowp = GT + (size_t)row * NGT + colt;
; #pragma unroll
;                 for (int bj = 0; bj < 2; ++bj) { f32x4 v0 = acc[ai][bj][m][0] * rs + bv[bj][0], v1 = acc[ai][bj][m][1] * rs + bv[bj][1];
;                     unsigned q0[4], q1[4];
; #pragma unroll
;                     for (int e = 0; e < 4; ++e) { q0[e] = (unsigned)fmaxf(sigmoidf_(v0[e]) * 255.0f + 0.5f, 1.0f); q1[e] = (unsigned)fmaxf(sigmoidf_(v1[e]) * 255.0f + 0.5f, 1.0f); }
;                     u32x2 w; w.x = q0[0] | (q0[1] << 8) | (q0[2] << 16) | (q0[3] << 24); w.y = q1[0] | (q1[1] << 8) | (q1[2] << 16) | (q1[3] << 24);
;                     *(u32x2*)(rowp + bj * HALF) = w; } }
	v_pk_fma_f32 v[204:205], v[44:45], v[30:31], v[12:13] op_sel:[0,0,0] op_sel_hi:[1,0,1]
	v_pk_fma_f32 v[206:207], v[46:47], v[30:31], v[14:15] op_sel:[0,0,0] op_sel_hi:[1,0,1]
	v_pk_fma_f32 v[208:209], v[48:49], v[30:31], v[16:17] op_sel:[0,0,0] op_sel_hi:[1,0,1]
	v_exp_f32_e32 v202, v202
	v_exp_f32_e32 v203, v203
	v_exp_f32_e32 v204, v204
	v_exp_f32_e32 v205, v205
	v_exp_f32_e32 v206, v206
	v_exp_f32_e32 v207, v207
	v_exp_f32_e32 v208, v208
	v_exp_f32_e32 v209, v209
	s_nop 0
	v_pk_fma_f32 v[202:203], v[202:203], s[98:99], s[98:99] op_sel_hi:[1,0,0] clamp
	v_pk_fma_f32 v[204:205], v[204:205], s[98:99], s[98:99] op_sel_hi:[1,0,0] clamp
	v_pk_fma_f32 v[206:207], v[206:207], s[98:99], s[98:99] op_sel_hi:[1,0,0] clamp
	v_pk_fma_f32 v[208:209], v[208:209], s[98:99], s[98:99] op_sel_hi:[1,0,0] clamp
	v_rcp_f32_e32 v202, v202
	v_rcp_f32_e32 v203, v203
	v_rcp_f32_e32 v204, v204
	v_rcp_f32_e32 v205, v205
	v_rcp_f32_e32 v206, v206
	v_rcp_f32_e32 v207, v207
	v_rcp_f32_e32 v208, v208
	v_rcp_f32_e32 v209, v209
	s_nop 0
	v_cvt_pk_u8_f32 v214, v206, 0, 0
	v_cvt_pk_u8_f32 v214, v207, 1, v214
	v_cvt_pk_u8_f32 v214, v208, 2, v214
	v_cvt_pk_u8_f32 v214, v209, 3, v214
	v_cvt_pk_u8_f32 v215, v202, 0, 0
	v_cvt_pk_u8_f32 v215, v203, 1, v215
	v_cvt_pk_u8_f32 v215, v204, 2, v215
	v_cvt_pk_u8_f32 v215, v205, 3, v215
	v_pk_fma_f32 v[202:203], v[50:51], v[30:31], v[2:3] op_sel:[0,1,0] op_sel_hi:[1,1,1]
	v_pk_fma_f32 v[204:205], v[52:53], v[30:31], v[4:5] op_sel:[0,1,0] op_sel_hi:[1,1,1]
	v_pk_fma_f32 v[206:207], v[54:55], v[30:31], v[6:7] op_sel:[0,1,0] op_sel_hi:[1,1,1]
	v_pk_fma_f32 v[208:209], v[56:57], v[30:31], v[8:9] op_sel:[0,1,0] op_sel_hi:[1,1,1]
	v_exp_f32_e32 v202, v202
	v_exp_f32_e32 v203, v203
	v_exp_f32_e32 v204, v204
	v_exp_f32_e32 v205, v205
	v_exp_f32_e32 v206, v206
	v_exp_f32_e32 v207, v207
	v_exp_f32_e32 v208, v208
	v_exp_f32_e32 v209, v209
	s_nop 0
	v_pk_fma_f32 v[202:203], v[202:203], s[98:99], s[98:99] op_sel_hi:[1,0,0] clamp
	v_pk_fma_f32 v[204:205], v[204:205], s[98:99], s[98:99] op_sel_hi:[1,0,0] clamp
	v_pk_fma_f32 v[206:207], v[206:207], s[98:99], s[98:99] op_sel_hi:[1,0,0] clamp
	v_pk_fma_f32 v[208:209], v[208:209], s[98:99], s[98:99] op_sel_hi:[1,0,0] clamp
	v_rcp_f32_e32 v202, v202
	v_rcp_f32_e32 v203, v203
	v_rcp_f32_e32 v204, v204
	v_rcp_f32_e32 v205, v205
	v_rcp_f32_e32 v206, v206
	v_rcp_f32_e32 v207, v207
	v_rcp_f32_e32 v208, v208
	v_rcp_f32_e32 v209, v209
	s_nop 0
	v_cvt_pk_u8_f32 v212, v206, 0, 0
	v_cvt_pk_u8_f32 v212, v207, 1, v212
	v_cvt_pk_u8_f32 v212, v208, 2, v212
	v_cvt_pk_u8_f32 v212, v209, 3, v212
	v_cvt_pk_u8_f32 v213, v202, 0, 0
	v_cvt_pk_u8_f32 v213, v203, 1, v213
	v_cvt_pk_u8_f32 v213, v204, 2, v213
	v_cvt_pk_u8_f32 v213, v205, 3, v213
	v_pk_fma_f32 v[202:203], v[34:35], v[30:31], v[2:3] op_sel:[0,0,0] op_sel_hi:[1,0,1]
	v_pk_fma_f32 v[204:205], v[36:37], v[30:31], v[4:5] op_sel:[0,0,0] op_sel_hi:[1,0,1]
	v_pk_fma_f32 v[206:207], v[38:39], v[30:31], v[6:7] op_sel:[0,0,0] op_sel_hi:[1,0,1]
	v_pk_fma_f32 v[208:209], v[40:41], v[30:31], v[8:9] op_sel:[0,0,0] op_sel_hi:[1,0,1]
	v_exp_f32_e32 v202, v202
	v_exp_f32_e32 v203, v203
	v_exp_f32_e32 v204, v204
	v_exp_f32_e32 v205, v205
	v_exp_f32_e32 v206, v206
	v_exp_f32_e32 v207, v207
	v_exp_f32_e32 v208, v208
	v_exp_f32_e32 v209, v209
	s_nop 0
	v_pk_fma_f32 v[202:203], v[202:203], s[98:99], s[98:99] op_sel_hi:[1,0,0] clamp
	v_pk_fma_f32 v[204:205], v[204:205], s[98:99], s[98:99] op_sel_hi:[1,0,0] clamp
	v_pk_fma_f32 v[206:207], v[206:207], s[98:99], s[98:99] op_sel_hi:[1,0,0] clamp
	v_pk_fma_f32 v[208:209], v[208:209], s[98:99], s[98:99] op_sel_hi:[1,0,0] clamp
	v_rcp_f32_e32 v202, v202
	v_rcp_f32_e32 v203, v203
	v_rcp_f32_e32 v204, v204
	v_rcp_f32_e32 v205, v205
	v_rcp_f32_e32 v206, v206
	v_rcp_f32_e32 v207, v207
	v_rcp_f32_e32 v208, v208
	v_rcp_f32_e32 v209, v209
	s_nop 0
	v_cvt_pk_u8_f32 v216, v206, 0, 0
	v_cvt_pk_u8_f32 v216, v207, 1, v216
	v_cvt_pk_u8_f32 v216, v208, 2, v216
	v_cvt_pk_u8_f32 v216, v209, 3, v216
	v_cvt_pk_u8_f32 v217, v202, 0, 0
	v_cvt_pk_u8_f32 v217, v203, 1, v217
	v_cvt_pk_u8_f32 v217, v204, 2, v217
	v_cvt_pk_u8_f32 v217, v205, 3, v217
	v_add_u32_e32 v223, 0xc000, v222
	global_store_dwordx4 v223, v[210:213], s[88:89]
	v_add_u32_e32 v223, 0xe000, v222
	global_store_dwordx4 v223, v[214:217], s[88:89]
	s_cbranch_execz .LBB0_574
